# P5 pass-1 K loop: dropped the four compiler-inserted vmcnt(0) drains before the transposed LDS reads (ring already ordered by vmcnt(8)+barrier like pass 2)
# speedup vs baseline: 1.0032x; 1.0029x over previous
.LBB0_1224:
	ds_read_b128 v[156:159], v139
	ds_read_b128 v[160:163], v139 offset:1024
	ds_read_b128 v[164:167], v139 offset:2048
	ds_read_b128 v[168:171], v139 offset:3072
	ds_read_b128 v[172:175], v141
	ds_read_b128 v[180:183], v141 offset:1024
	ds_read_b128 v[184:187], v141 offset:2048
	ds_read_b128 v[188:191], v141 offset:3072
	s_add_u32 s22, s82, s57
	s_addc_u32 s23, s83, s58
	s_waitcnt lgkmcnt(0)
	s_add_u32 s85, s82, s55
	s_addc_u32 s86, s83, s56
	s_cmp_eq_u32 s59, 4
	s_cselect_b64 vcc, -1, 0
	s_and_b64 s[20:21], vcc, exec
	s_mov_b32 s20, 0x200000
	s_cselect_b32 s25, s47, s23
	s_cselect_b32 s24, s46, s22
	s_cselect_b32 s22, 0x80, s20
	s_mov_b32 s23, 0x20000
	s_cselect_b32 s20, s48, s85
	s_cselect_b32 s21, s49, s86
	s_cselect_b32 s85, s23, 0x100
	s_add_u32 s22, s24, s22
	v_cndmask_b32_e32 v207, v138, v134, vcc
	v_cndmask_b32_e32 v209, v140, v136, vcc
	s_addc_u32 s23, s25, 0
	s_mov_b32 m0, s60
	v_lshl_add_u64 v[176:177], s[82:83], 0, v[142:143]
	ds_read_b64_tr_b16 v[192:193], v146
	ds_read_b64_tr_b16 v[194:195], v147 offset:1024
	ds_read_b64_tr_b16 v[198:199], v147 offset:9216
	ds_read_b64_tr_b16 v[196:197], v146 offset:8192
	ds_read_b64_tr_b16 v[200:201], v148
	ds_read_b64_tr_b16 v[202:203], v149 offset:1024
	ds_read_b64_tr_b16 v[212:213], v149 offset:9216
	ds_read_b64_tr_b16 v[210:211], v148 offset:8192
	ds_read_b64_tr_b16 v[214:215], v150
	ds_read_b64_tr_b16 v[216:217], v151 offset:1024
	ds_read_b64_tr_b16 v[220:221], v151 offset:9216
	ds_read_b64_tr_b16 v[218:219], v150 offset:8192
	ds_read_b64_tr_b16 v[222:223], v152
	ds_read_b64_tr_b16 v[224:225], v153 offset:1024
	ds_read_b64_tr_b16 v[228:229], v153 offset:9216
	ds_read_b64_tr_b16 v[226:227], v152 offset:8192
	global_load_lds_dwordx4 v[176:177], off
	v_lshl_add_u64 v[176:177], s[82:83], 0, v[144:145]
	s_mov_b32 m0, s61
	s_nop 0
	global_load_lds_dwordx4 v[176:177], off
	s_waitcnt vmcnt(8)
	s_waitcnt lgkmcnt(0)
	s_barrier
	s_setprio 1
	s_waitcnt lgkmcnt(0)
	v_mfma_f32_16x16x32_bf16 v[66:69], v[156:159], v[192:195], v[66:69]
	v_mfma_f32_16x16x32_bf16 v[74:77], v[164:167], v[192:195], v[74:77]
	v_mfma_f32_16x16x32_bf16 v[90:93], v[156:159], v[200:203], v[90:93]
	v_mfma_f32_16x16x32_bf16 v[94:97], v[164:167], v[200:203], v[94:97]
	v_mfma_f32_16x16x32_bf16 v[110:113], v[156:159], v[214:217], v[110:113]
	v_mfma_f32_16x16x32_bf16 v[118:121], v[164:167], v[214:217], v[118:121]
	v_mfma_f32_16x16x32_bf16 v[114:117], v[156:159], v[222:225], v[114:117]
	v_mfma_f32_16x16x32_bf16 v[106:109], v[164:167], v[222:225], v[106:109]
	v_mfma_f32_16x16x32_bf16 v[66:69], v[160:163], v[196:199], v[66:69]
	v_mfma_f32_16x16x32_bf16 v[74:77], v[168:171], v[196:199], v[74:77]
	v_mfma_f32_16x16x32_bf16 v[90:93], v[160:163], v[210:213], v[90:93]
	v_mfma_f32_16x16x32_bf16 v[94:97], v[168:171], v[210:213], v[94:97]
	v_mfma_f32_16x16x32_bf16 v[110:113], v[160:163], v[218:221], v[110:113]
	v_mfma_f32_16x16x32_bf16 v[118:121], v[168:171], v[218:221], v[118:121]
	v_mfma_f32_16x16x32_bf16 v[114:117], v[160:163], v[226:229], v[114:117]
	v_mfma_f32_16x16x32_bf16 v[106:109], v[168:171], v[226:229], v[106:109]
	s_setprio 0
	s_setprio 1
	v_mfma_f32_16x16x32_bf16 v[78:81], v[172:175], v[192:195], v[78:81]
	v_mfma_f32_16x16x32_bf16 v[86:89], v[184:187], v[192:195], v[86:89]
	v_mfma_f32_16x16x32_bf16 v[98:101], v[172:175], v[200:203], v[98:101]
	v_mfma_f32_16x16x32_bf16 v[102:105], v[184:187], v[200:203], v[102:105]
	v_mfma_f32_16x16x32_bf16 v[122:125], v[172:175], v[214:217], v[122:125]
	v_mfma_f32_16x16x32_bf16 v[126:129], v[184:187], v[214:217], v[126:129]
	v_mfma_f32_16x16x32_bf16 v[82:85], v[172:175], v[222:225], v[82:85]
	v_mfma_f32_16x16x32_bf16 v[70:73], v[184:187], v[222:225], v[70:73]
	v_mfma_f32_16x16x32_bf16 v[78:81], v[180:183], v[196:199], v[78:81]
	v_mfma_f32_16x16x32_bf16 v[86:89], v[188:191], v[196:199], v[86:89]
	v_mfma_f32_16x16x32_bf16 v[98:101], v[180:183], v[210:213], v[98:101]
	v_mfma_f32_16x16x32_bf16 v[102:105], v[188:191], v[210:213], v[102:105]
	v_mfma_f32_16x16x32_bf16 v[122:125], v[180:183], v[218:221], v[122:125]
	v_mfma_f32_16x16x32_bf16 v[126:129], v[188:191], v[218:221], v[126:129]
	v_mfma_f32_16x16x32_bf16 v[82:85], v[180:183], v[226:229], v[82:85]
	v_mfma_f32_16x16x32_bf16 v[70:73], v[188:191], v[226:229], v[70:73]
	s_setprio 0
	s_barrier
	s_mov_b32 m0, s62
	v_lshl_add_u64 v[176:177], s[20:21], 0, v[130:131]
	s_add_u32 s86, s20, 0x20000
	ds_read_b64_tr_b16 v[192:193], v146 offset:16384
	ds_read_b64_tr_b16 v[194:195], v147 offset:17408
	ds_read_b64_tr_b16 v[198:199], v147 offset:25600
	ds_read_b64_tr_b16 v[196:197], v146 offset:24576
	ds_read_b64_tr_b16 v[200:201], v148 offset:16384
	ds_read_b64_tr_b16 v[202:203], v149 offset:17408
	ds_read_b64_tr_b16 v[212:213], v149 offset:25600
	ds_read_b64_tr_b16 v[210:211], v148 offset:24576
	ds_read_b64_tr_b16 v[214:215], v150 offset:16384
	ds_read_b64_tr_b16 v[216:217], v151 offset:17408
	ds_read_b64_tr_b16 v[220:221], v151 offset:25600
	ds_read_b64_tr_b16 v[218:219], v150 offset:24576
	ds_read_b64_tr_b16 v[222:223], v152 offset:16384
	ds_read_b64_tr_b16 v[224:225], v153 offset:17408
	ds_read_b64_tr_b16 v[228:229], v153 offset:25600
	ds_read_b64_tr_b16 v[226:227], v152 offset:24576
	global_load_lds_dwordx4 v[176:177], off
	v_lshl_add_u64 v[230:231], s[20:21], 0, v[132:133]
	s_mov_b32 m0, s63
	s_addc_u32 s87, s21, 0
	global_load_lds_dwordx4 v[230:231], off
	v_lshl_add_u64 v[232:233], s[86:87], 0, v[130:131]
	s_mov_b32 m0, s64
	s_nop 0
	global_load_lds_dwordx4 v[232:233], off
	v_lshl_add_u64 v[232:233], s[86:87], 0, v[132:133]
	s_mov_b32 m0, s65
	s_nop 0
	global_load_lds_dwordx4 v[232:233], off
	s_mov_b32 m0, s13
	s_nop 0
	global_load_lds_dwordx4 v207, s[24:25]
	s_mov_b32 m0, s15
	s_nop 0
	global_load_lds_dwordx4 v209, s[24:25]
	s_waitcnt vmcnt(8)
	s_waitcnt lgkmcnt(0)
	s_barrier
	s_setprio 1
	s_waitcnt lgkmcnt(0)
	v_mfma_f32_16x16x32_bf16 v[62:65], v[156:159], v[192:195], v[62:65]
	v_mfma_f32_16x16x32_bf16 v[58:61], v[164:167], v[192:195], v[58:61]
	v_mfma_f32_16x16x32_bf16 v[46:49], v[156:159], v[200:203], v[46:49]
	v_mfma_f32_16x16x32_bf16 v[42:45], v[164:167], v[200:203], v[42:45]
	v_mfma_f32_16x16x32_bf16 v[26:29], v[156:159], v[214:217], v[26:29]
	v_mfma_f32_16x16x32_bf16 v[18:21], v[164:167], v[214:217], v[18:21]
	v_mfma_f32_16x16x32_bf16 v[10:13], v[156:159], v[222:225], v[10:13]
	v_mfma_f32_16x16x32_bf16 v[2:5], v[164:167], v[222:225], v[2:5]
	v_mfma_f32_16x16x32_bf16 v[62:65], v[160:163], v[196:199], v[62:65]
	v_mfma_f32_16x16x32_bf16 v[58:61], v[168:171], v[196:199], v[58:61]
	v_mfma_f32_16x16x32_bf16 v[46:49], v[160:163], v[210:213], v[46:49]
	v_mfma_f32_16x16x32_bf16 v[42:45], v[168:171], v[210:213], v[42:45]
	v_mfma_f32_16x16x32_bf16 v[26:29], v[160:163], v[218:221], v[26:29]
	v_mfma_f32_16x16x32_bf16 v[18:21], v[168:171], v[218:221], v[18:21]
	v_mfma_f32_16x16x32_bf16 v[10:13], v[160:163], v[226:229], v[10:13]
	v_mfma_f32_16x16x32_bf16 v[2:5], v[168:171], v[226:229], v[2:5]
	s_setprio 0
	s_setprio 1
	v_mfma_f32_16x16x32_bf16 v[54:57], v[172:175], v[192:195], v[54:57]
	v_mfma_f32_16x16x32_bf16 v[50:53], v[184:187], v[192:195], v[50:53]
	v_mfma_f32_16x16x32_bf16 v[38:41], v[172:175], v[200:203], v[38:41]
	v_mfma_f32_16x16x32_bf16 v[34:37], v[184:187], v[200:203], v[34:37]
	v_mfma_f32_16x16x32_bf16 v[30:33], v[172:175], v[214:217], v[30:33]
	v_mfma_f32_16x16x32_bf16 v[22:25], v[184:187], v[214:217], v[22:25]
	v_mfma_f32_16x16x32_bf16 v[14:17], v[172:175], v[222:225], v[14:17]
	v_mfma_f32_16x16x32_bf16 v[6:9], v[184:187], v[222:225], v[6:9]
	v_mfma_f32_16x16x32_bf16 v[54:57], v[180:183], v[196:199], v[54:57]
	v_mfma_f32_16x16x32_bf16 v[50:53], v[188:191], v[196:199], v[50:53]
	v_mfma_f32_16x16x32_bf16 v[38:41], v[180:183], v[210:213], v[38:41]
	v_mfma_f32_16x16x32_bf16 v[34:37], v[188:191], v[210:213], v[34:37]
	v_mfma_f32_16x16x32_bf16 v[30:33], v[180:183], v[218:221], v[30:33]
	v_mfma_f32_16x16x32_bf16 v[22:25], v[188:191], v[218:221], v[22:25]
	v_mfma_f32_16x16x32_bf16 v[14:17], v[180:183], v[226:229], v[14:17]
	v_mfma_f32_16x16x32_bf16 v[6:9], v[188:191], v[226:229], v[6:9]
	s_setprio 0
	s_barrier
	ds_read_b128 v[156:159], v154
	ds_read_b128 v[160:163], v154 offset:1024
	ds_read_b128 v[164:167], v154 offset:2048
	ds_read_b128 v[168:171], v154 offset:3072
	ds_read_b128 v[172:175], v155
	ds_read_b128 v[180:183], v155 offset:1024
	ds_read_b128 v[184:187], v155 offset:2048
	ds_read_b128 v[188:191], v155 offset:3072
	s_add_u32 s24, s24, s85
	s_addc_u32 s25, s25, 0
	s_mov_b32 m0, s43
	ds_read_b64_tr_b16 v[192:193], v146 offset:32768
	ds_read_b64_tr_b16 v[194:195], v147 offset:33792
	ds_read_b64_tr_b16 v[198:199], v147 offset:41984
	ds_read_b64_tr_b16 v[196:197], v146 offset:40960
	ds_read_b64_tr_b16 v[200:201], v148 offset:32768
	ds_read_b64_tr_b16 v[202:203], v149 offset:33792
	ds_read_b64_tr_b16 v[212:213], v149 offset:41984
	ds_read_b64_tr_b16 v[210:211], v148 offset:40960
	ds_read_b64_tr_b16 v[214:215], v150 offset:32768
	ds_read_b64_tr_b16 v[216:217], v151 offset:33792
	ds_read_b64_tr_b16 v[220:221], v151 offset:41984
	ds_read_b64_tr_b16 v[218:219], v150 offset:40960
	ds_read_b64_tr_b16 v[222:223], v152 offset:32768
	ds_read_b64_tr_b16 v[224:225], v153 offset:33792
	ds_read_b64_tr_b16 v[228:229], v153 offset:41984
	ds_read_b64_tr_b16 v[226:227], v152 offset:40960
	global_load_lds_dwordx4 v207, s[24:25]
	s_mov_b32 m0, s45
	s_nop 0
	global_load_lds_dwordx4 v209, s[24:25]
	s_waitcnt vmcnt(8)
	s_waitcnt lgkmcnt(0)
	s_barrier
	s_setprio 1
	s_waitcnt lgkmcnt(0)
	v_mfma_f32_16x16x32_bf16 v[66:69], v[156:159], v[192:195], v[66:69]
	v_mfma_f32_16x16x32_bf16 v[74:77], v[164:167], v[192:195], v[74:77]
	v_mfma_f32_16x16x32_bf16 v[90:93], v[156:159], v[200:203], v[90:93]
	v_mfma_f32_16x16x32_bf16 v[94:97], v[164:167], v[200:203], v[94:97]
	v_mfma_f32_16x16x32_bf16 v[110:113], v[156:159], v[214:217], v[110:113]
	v_mfma_f32_16x16x32_bf16 v[118:121], v[164:167], v[214:217], v[118:121]
	v_mfma_f32_16x16x32_bf16 v[114:117], v[156:159], v[222:225], v[114:117]
	v_mfma_f32_16x16x32_bf16 v[106:109], v[164:167], v[222:225], v[106:109]
	v_mfma_f32_16x16x32_bf16 v[66:69], v[160:163], v[196:199], v[66:69]
	v_mfma_f32_16x16x32_bf16 v[74:77], v[168:171], v[196:199], v[74:77]
	v_mfma_f32_16x16x32_bf16 v[90:93], v[160:163], v[210:213], v[90:93]
	v_mfma_f32_16x16x32_bf16 v[94:97], v[168:171], v[210:213], v[94:97]
	v_mfma_f32_16x16x32_bf16 v[110:113], v[160:163], v[218:221], v[110:113]
	v_mfma_f32_16x16x32_bf16 v[118:121], v[168:171], v[218:221], v[118:121]
	v_mfma_f32_16x16x32_bf16 v[114:117], v[160:163], v[226:229], v[114:117]
	v_mfma_f32_16x16x32_bf16 v[106:109], v[168:171], v[226:229], v[106:109]
	s_setprio 0
	s_setprio 1
	v_mfma_f32_16x16x32_bf16 v[78:81], v[172:175], v[192:195], v[78:81]
	v_mfma_f32_16x16x32_bf16 v[86:89], v[184:187], v[192:195], v[86:89]
	v_mfma_f32_16x16x32_bf16 v[98:101], v[172:175], v[200:203], v[98:101]
	v_mfma_f32_16x16x32_bf16 v[102:105], v[184:187], v[200:203], v[102:105]
	v_mfma_f32_16x16x32_bf16 v[122:125], v[172:175], v[214:217], v[122:125]
	v_mfma_f32_16x16x32_bf16 v[126:129], v[184:187], v[214:217], v[126:129]
	v_mfma_f32_16x16x32_bf16 v[82:85], v[172:175], v[222:225], v[82:85]
	v_mfma_f32_16x16x32_bf16 v[70:73], v[184:187], v[222:225], v[70:73]
	v_mfma_f32_16x16x32_bf16 v[78:81], v[180:183], v[196:199], v[78:81]
	v_mfma_f32_16x16x32_bf16 v[86:89], v[188:191], v[196:199], v[86:89]
	v_mfma_f32_16x16x32_bf16 v[98:101], v[180:183], v[210:213], v[98:101]
	v_mfma_f32_16x16x32_bf16 v[102:105], v[188:191], v[210:213], v[102:105]
	v_mfma_f32_16x16x32_bf16 v[122:125], v[180:183], v[218:221], v[122:125]
	v_mfma_f32_16x16x32_bf16 v[126:129], v[188:191], v[218:221], v[126:129]
	v_mfma_f32_16x16x32_bf16 v[82:85], v[180:183], v[226:229], v[82:85]
	v_mfma_f32_16x16x32_bf16 v[70:73], v[188:191], v[226:229], v[70:73]
	s_setprio 0
	s_barrier
	s_mov_b32 m0, s66
	v_lshl_add_u64 v[176:177], v[176:177], 0, s[16:17]
	s_add_u32 s20, s20, 0x20080
	ds_read_b64_tr_b16 v[192:193], v146 offset:49152
	ds_read_b64_tr_b16 v[194:195], v147 offset:50176
	ds_read_b64_tr_b16 v[198:199], v147 offset:58368
	ds_read_b64_tr_b16 v[196:197], v146 offset:57344
	ds_read_b64_tr_b16 v[200:201], v148 offset:49152
	ds_read_b64_tr_b16 v[202:203], v149 offset:50176
	ds_read_b64_tr_b16 v[212:213], v149 offset:58368
	ds_read_b64_tr_b16 v[210:211], v148 offset:57344
	ds_read_b64_tr_b16 v[214:215], v150 offset:49152
	ds_read_b64_tr_b16 v[216:217], v151 offset:50176
	ds_read_b64_tr_b16 v[220:221], v151 offset:58368
	ds_read_b64_tr_b16 v[218:219], v150 offset:57344
	ds_read_b64_tr_b16 v[222:223], v152 offset:49152
	ds_read_b64_tr_b16 v[224:225], v153 offset:50176
	ds_read_b64_tr_b16 v[228:229], v153 offset:58368
	ds_read_b64_tr_b16 v[226:227], v152 offset:57344
	global_load_lds_dwordx4 v[176:177], off
	v_lshl_add_u64 v[176:177], v[230:231], 0, s[16:17]
	s_mov_b32 m0, s67
	s_addc_u32 s21, s21, 0
	global_load_lds_dwordx4 v[176:177], off
	v_lshl_add_u64 v[176:177], s[20:21], 0, v[130:131]
	s_mov_b32 m0, s36
	s_nop 0
	global_load_lds_dwordx4 v[176:177], off
	v_lshl_add_u64 v[176:177], s[20:21], 0, v[132:133]
	s_mov_b32 m0, s37
	s_nop 0
	global_load_lds_dwordx4 v[176:177], off
	s_mov_b32 m0, s53
	s_nop 0
	global_load_lds_dwordx4 v207, s[22:23]
	s_mov_b32 m0, s54
	s_nop 0
	global_load_lds_dwordx4 v209, s[22:23]
	s_waitcnt vmcnt(8)
	s_waitcnt lgkmcnt(0)
	s_barrier
	s_setprio 1
	s_waitcnt lgkmcnt(0)
	v_mfma_f32_16x16x32_bf16 v[62:65], v[156:159], v[192:195], v[62:65]
	v_mfma_f32_16x16x32_bf16 v[58:61], v[164:167], v[192:195], v[58:61]
	v_mfma_f32_16x16x32_bf16 v[46:49], v[156:159], v[200:203], v[46:49]
	v_mfma_f32_16x16x32_bf16 v[42:45], v[164:167], v[200:203], v[42:45]
	v_mfma_f32_16x16x32_bf16 v[26:29], v[156:159], v[214:217], v[26:29]
	v_mfma_f32_16x16x32_bf16 v[18:21], v[164:167], v[214:217], v[18:21]
	v_mfma_f32_16x16x32_bf16 v[10:13], v[156:159], v[222:225], v[10:13]
	v_mfma_f32_16x16x32_bf16 v[2:5], v[164:167], v[222:225], v[2:5]
	v_mfma_f32_16x16x32_bf16 v[62:65], v[160:163], v[196:199], v[62:65]
	v_mfma_f32_16x16x32_bf16 v[58:61], v[168:171], v[196:199], v[58:61]
	v_mfma_f32_16x16x32_bf16 v[46:49], v[160:163], v[210:213], v[46:49]
	v_mfma_f32_16x16x32_bf16 v[42:45], v[168:171], v[210:213], v[42:45]
	v_mfma_f32_16x16x32_bf16 v[26:29], v[160:163], v[218:221], v[26:29]
	v_mfma_f32_16x16x32_bf16 v[18:21], v[168:171], v[218:221], v[18:21]
	v_mfma_f32_16x16x32_bf16 v[10:13], v[160:163], v[226:229], v[10:13]
	v_mfma_f32_16x16x32_bf16 v[2:5], v[168:171], v[226:229], v[2:5]
	s_setprio 0
	s_setprio 1
	v_mfma_f32_16x16x32_bf16 v[54:57], v[172:175], v[192:195], v[54:57]
	v_mfma_f32_16x16x32_bf16 v[50:53], v[184:187], v[192:195], v[50:53]
	v_mfma_f32_16x16x32_bf16 v[38:41], v[172:175], v[200:203], v[38:41]
	v_mfma_f32_16x16x32_bf16 v[34:37], v[184:187], v[200:203], v[34:37]
	v_mfma_f32_16x16x32_bf16 v[30:33], v[172:175], v[214:217], v[30:33]
	v_mfma_f32_16x16x32_bf16 v[22:25], v[184:187], v[214:217], v[22:25]
	v_mfma_f32_16x16x32_bf16 v[14:17], v[172:175], v[222:225], v[14:17]
	v_mfma_f32_16x16x32_bf16 v[6:9], v[184:187], v[222:225], v[6:9]
	v_mfma_f32_16x16x32_bf16 v[54:57], v[180:183], v[196:199], v[54:57]
	v_mfma_f32_16x16x32_bf16 v[50:53], v[188:191], v[196:199], v[50:53]
	v_mfma_f32_16x16x32_bf16 v[38:41], v[180:183], v[210:213], v[38:41]
	v_mfma_f32_16x16x32_bf16 v[34:37], v[188:191], v[210:213], v[34:37]
	v_mfma_f32_16x16x32_bf16 v[30:33], v[180:183], v[218:221], v[30:33]
	v_mfma_f32_16x16x32_bf16 v[22:25], v[188:191], v[218:221], v[22:25]
	v_mfma_f32_16x16x32_bf16 v[14:17], v[180:183], v[226:229], v[14:17]
	v_mfma_f32_16x16x32_bf16 v[6:9], v[188:191], v[226:229], v[6:9]
	s_setprio 0
	s_barrier
	s_add_i32 s59, s59, 2
	s_add_u32 s55, s55, 0x100
	s_addc_u32 s56, s56, 0
	s_add_u32 s57, s57, 0x400000
	s_addc_u32 s58, s58, 0
	v_lshl_add_u64 v[142:143], v[142:143], 0, s[18:19]
	s_cmp_gt_u32 s59, 5
	v_lshl_add_u64 v[144:145], v[144:145], 0, s[18:19]
	s_cbranch_scc0 .LBB0_1224
	s_cmpk_lt_u32 s35, 0x100
	s_cbranch_scc0 .LBB0_1227
	s_barrier
